# attention: fast path for unmasked key tiles with a decay-tracking softmax reference (reference advances by the forget-gate decay across the tile, alpha=2^-D known before QK^T, bias minus reference fed
# speedup vs baseline: 1.0117x; 1.0072x over previous
.LBB0_873:
	s_cmpk_eq_i32 s71, 0xffd0
	s_cselect_b64 s[34:35], -1, 0
	s_and_b64 s[4:5], s[34:35], exec
	s_cselect_b32 s84, 0, s71
	s_cmp_gt_i32 s84, s29
	s_cselect_b64 s[4:5], -1, 0
	s_or_b64 s[4:5], s[58:59], s[4:5]
	s_and_b64 vcc, exec, s[4:5]
	s_cbranch_vccnz .LBB0_883
	s_add_i32 s4, s84, 63
	s_cmp_gt_i32 s4, s95
	s_cselect_b64 s[4:5], -1, 0
	s_or_b64 s[4:5], s[34:35], s[4:5]
	s_and_b64 vcc, exec, s[4:5]
	s_cbranch_vccnz .Lattn_orig
	ds_read_b128 v[88:91], v221
	ds_read_b128 v[92:95], v221 offset:64
	ds_read_b128 v[164:167], v221 offset:576
	ds_read_b128 v[168:171], v221 offset:640
	ds_read_b128 v[172:175], v221 offset:4608
	ds_read_b128 v[236:239], v221 offset:4672
	ds_read_b128 v[240:243], v221 offset:5184
	ds_read_b128 v[160:163], v221 offset:5248
	v_readlane_b32 s4, v84, 0
	v_readlane_b32 s5, v75, 63
	v_pk_add_f32 v[116:117], v[140:141], v[84:85] neg_lo:[0,1] neg_hi:[0,1]
	v_pk_add_f32 v[118:119], v[140:141], v[86:87] neg_lo:[0,1] neg_hi:[0,1]
	v_pk_add_f32 v[100:101], v[142:143], v[84:85] neg_lo:[0,1] neg_hi:[0,1]
	v_pk_add_f32 v[102:103], v[142:143], v[86:87] neg_lo:[0,1] neg_hi:[0,1]
	v_pk_add_f32 v[112:113], v[140:141], v[76:77] neg_lo:[0,1] neg_hi:[0,1]
	v_pk_add_f32 v[114:115], v[140:141], v[78:79] neg_lo:[0,1] neg_hi:[0,1]
	v_pk_add_f32 v[96:97], v[142:143], v[76:77] neg_lo:[0,1] neg_hi:[0,1]
	v_pk_add_f32 v[98:99], v[142:143], v[78:79] neg_lo:[0,1] neg_hi:[0,1]
	v_pk_add_f32 v[108:109], v[140:141], v[80:81] neg_lo:[0,1] neg_hi:[0,1]
	v_pk_add_f32 v[110:111], v[140:141], v[82:83] neg_lo:[0,1] neg_hi:[0,1]
	v_pk_add_f32 v[244:245], v[142:143], v[80:81] neg_lo:[0,1] neg_hi:[0,1]
	v_pk_add_f32 v[246:247], v[142:143], v[82:83] neg_lo:[0,1] neg_hi:[0,1]
	v_pk_add_f32 v[104:105], v[140:141], v[72:73] neg_lo:[0,1] neg_hi:[0,1]
	v_pk_add_f32 v[106:107], v[140:141], v[74:75] neg_lo:[0,1] neg_hi:[0,1]
	v_pk_add_f32 v[248:249], v[142:143], v[72:73] neg_lo:[0,1] neg_hi:[0,1]
	v_pk_add_f32 v[250:251], v[142:143], v[74:75] neg_lo:[0,1] neg_hi:[0,1]
	v_mov_b32_e32 v234, s5
	v_sub_f32_e32 v234, s4, v234
	v_add_f32_e32 v231, v227, v234
	v_add_f32_e32 v230, v226, v234
	v_exp_f32_e64 v232, -v234
	v_pk_add_f32 v[116:117], v[116:117], v[230:231] op_sel:[0,1] op_sel_hi:[1,1] neg_lo:[0,1] neg_hi:[0,1]
	v_pk_add_f32 v[118:119], v[118:119], v[230:231] op_sel:[0,1] op_sel_hi:[1,1] neg_lo:[0,1] neg_hi:[0,1]
	v_pk_add_f32 v[100:101], v[100:101], v[230:231] op_sel_hi:[1,0] neg_lo:[0,1] neg_hi:[0,1]
	v_pk_add_f32 v[102:103], v[102:103], v[230:231] op_sel_hi:[1,0] neg_lo:[0,1] neg_hi:[0,1]
	v_pk_add_f32 v[112:113], v[112:113], v[230:231] op_sel:[0,1] op_sel_hi:[1,1] neg_lo:[0,1] neg_hi:[0,1]
	v_pk_add_f32 v[114:115], v[114:115], v[230:231] op_sel:[0,1] op_sel_hi:[1,1] neg_lo:[0,1] neg_hi:[0,1]
	v_pk_add_f32 v[96:97], v[96:97], v[230:231] op_sel_hi:[1,0] neg_lo:[0,1] neg_hi:[0,1]
	v_pk_add_f32 v[98:99], v[98:99], v[230:231] op_sel_hi:[1,0] neg_lo:[0,1] neg_hi:[0,1]
	v_pk_add_f32 v[108:109], v[108:109], v[230:231] op_sel:[0,1] op_sel_hi:[1,1] neg_lo:[0,1] neg_hi:[0,1]
	v_pk_add_f32 v[110:111], v[110:111], v[230:231] op_sel:[0,1] op_sel_hi:[1,1] neg_lo:[0,1] neg_hi:[0,1]
	v_pk_add_f32 v[244:245], v[244:245], v[230:231] op_sel_hi:[1,0] neg_lo:[0,1] neg_hi:[0,1]
	v_pk_add_f32 v[246:247], v[246:247], v[230:231] op_sel_hi:[1,0] neg_lo:[0,1] neg_hi:[0,1]
	v_pk_add_f32 v[104:105], v[104:105], v[230:231] op_sel:[0,1] op_sel_hi:[1,1] neg_lo:[0,1] neg_hi:[0,1]
	v_pk_add_f32 v[106:107], v[106:107], v[230:231] op_sel:[0,1] op_sel_hi:[1,1] neg_lo:[0,1] neg_hi:[0,1]
	v_pk_add_f32 v[248:249], v[248:249], v[230:231] op_sel_hi:[1,0] neg_lo:[0,1] neg_hi:[0,1]
	v_pk_add_f32 v[250:251], v[250:251], v[230:231] op_sel_hi:[1,0] neg_lo:[0,1] neg_hi:[0,1]
	s_waitcnt lgkmcnt(4)
	v_mfma_f32_16x16x32_bf16 v[116:119], v[88:91], v[0:3], v[116:119]
	v_mfma_f32_16x16x32_bf16 v[100:103], v[88:91], v[8:11], v[100:103]
	v_mfma_f32_16x16x32_bf16 v[112:115], v[164:167], v[0:3], v[112:115]
	v_mfma_f32_16x16x32_bf16 v[96:99], v[164:167], v[8:11], v[96:99]
	v_mfma_f32_16x16x32_bf16 v[116:119], v[92:95], v[4:7], v[116:119]
	v_mfma_f32_16x16x32_bf16 v[100:103], v[92:95], v[12:15], v[100:103]
	v_mfma_f32_16x16x32_bf16 v[112:115], v[168:171], v[4:7], v[112:115]
	v_mfma_f32_16x16x32_bf16 v[96:99], v[168:171], v[12:15], v[96:99]
	s_waitcnt lgkmcnt(0)
	v_mfma_f32_16x16x32_bf16 v[108:111], v[172:175], v[0:3], v[108:111]
	v_mfma_f32_16x16x32_bf16 v[244:247], v[172:175], v[8:11], v[244:247]
	v_mfma_f32_16x16x32_bf16 v[104:107], v[240:243], v[0:3], v[104:107]
	v_mfma_f32_16x16x32_bf16 v[248:251], v[240:243], v[8:11], v[248:251]
	v_mfma_f32_16x16x32_bf16 v[108:111], v[236:239], v[4:7], v[108:111]
	v_mfma_f32_16x16x32_bf16 v[244:247], v[236:239], v[12:15], v[244:247]
	v_mfma_f32_16x16x32_bf16 v[104:107], v[160:163], v[4:7], v[104:107]
	v_mfma_f32_16x16x32_bf16 v[248:251], v[160:163], v[12:15], v[248:251]
	ds_read_b128 v[88:91], v222 offset:9216
	ds_read_b128 v[92:95], v222 offset:9280
	ds_read_b128 v[164:167], v222 offset:11520
	ds_read_b128 v[168:171], v222 offset:11584
	ds_read_b128 v[172:175], v222 offset:13824
	ds_read_b128 v[236:239], v222 offset:13888
	ds_read_b128 v[240:243], v223 offset:9216
	ds_read_b128 v[160:163], v223 offset:9280
	v_max3_f32 v228, v116, v117, v118
	v_max3_f32 v229, v100, v101, v102
	v_max3_f32 v228, v228, v119, v112
	v_max3_f32 v229, v229, v103, v96
	v_max3_f32 v228, v228, v113, v114
	v_max3_f32 v229, v229, v97, v98
	v_max3_f32 v228, v228, v115, v108
	v_max3_f32 v229, v229, v99, v244
	v_max3_f32 v228, v228, v109, v110
	v_max3_f32 v229, v229, v245, v246
	v_max3_f32 v228, v228, v111, v104
	v_max3_f32 v229, v229, v247, v248
	v_max3_f32 v228, v228, v105, v106
	v_max3_f32 v229, v229, v249, v250
	v_max_f32_e32 v228, v228, v107
	v_max_f32_e32 v229, v229, v251
	v_max_f32_e32 v202, v228, v229
	v_cmp_lt_f32_e32 vcc, 0x42800000, v202
	s_cbranch_vccnz .Lattn_orig
	v_mov_b32_e32 v226, v230
	v_mov_b32_e32 v227, v231
	v_pk_mul_f32 v[52:53], v[52:53], v[232:233] op_sel_hi:[1,0]
	v_pk_mul_f32 v[54:55], v[54:55], v[232:233] op_sel_hi:[1,0]
	v_pk_mul_f32 v[44:45], v[44:45], v[232:233] op_sel_hi:[1,0]
	v_pk_mul_f32 v[46:47], v[46:47], v[232:233] op_sel_hi:[1,0]
	v_pk_mul_f32 v[40:41], v[40:41], v[232:233] op_sel_hi:[1,0]
	v_pk_mul_f32 v[42:43], v[42:43], v[232:233] op_sel_hi:[1,0]
	v_pk_mul_f32 v[48:49], v[48:49], v[232:233] op_sel_hi:[1,0]
	v_pk_mul_f32 v[50:51], v[50:51], v[232:233] op_sel_hi:[1,0]
	v_pk_mul_f32 v[36:37], v[36:37], v[232:233] op_sel_hi:[1,0]
	v_pk_mul_f32 v[38:39], v[38:39], v[232:233] op_sel_hi:[1,0]
	v_pk_mul_f32 v[28:29], v[28:29], v[232:233] op_sel_hi:[1,0]
	v_pk_mul_f32 v[30:31], v[30:31], v[232:233] op_sel_hi:[1,0]
	v_pk_mul_f32 v[16:17], v[16:17], v[232:233] op_sel_hi:[1,0]
	v_pk_mul_f32 v[18:19], v[18:19], v[232:233] op_sel_hi:[1,0]
	v_pk_mul_f32 v[32:33], v[32:33], v[232:233] op_sel_hi:[1,0]
	v_pk_mul_f32 v[34:35], v[34:35], v[232:233] op_sel_hi:[1,0]
	v_exp_f32_e32 v116, v116
	v_exp_f32_e32 v117, v117
	v_exp_f32_e32 v118, v118
	v_exp_f32_e32 v119, v119
	v_exp_f32_e32 v112, v112
	v_exp_f32_e32 v113, v113
	v_exp_f32_e32 v114, v114
	v_exp_f32_e32 v115, v115
	v_exp_f32_e32 v108, v108
	v_exp_f32_e32 v109, v109
	v_exp_f32_e32 v110, v110
	v_exp_f32_e32 v111, v111
	v_exp_f32_e32 v104, v104
	v_exp_f32_e32 v105, v105
	v_exp_f32_e32 v106, v106
	v_exp_f32_e32 v107, v107
	v_exp_f32_e32 v100, v100
	v_exp_f32_e32 v101, v101
	v_exp_f32_e32 v102, v102
	v_exp_f32_e32 v103, v103
	v_exp_f32_e32 v96, v96
	v_exp_f32_e32 v97, v97
	v_exp_f32_e32 v98, v98
	v_exp_f32_e32 v99, v99
	v_exp_f32_e32 v244, v244
	v_exp_f32_e32 v245, v245
	v_exp_f32_e32 v246, v246
	v_exp_f32_e32 v247, v247
	v_exp_f32_e32 v248, v248
	v_exp_f32_e32 v249, v249
	v_exp_f32_e32 v250, v250
	v_exp_f32_e32 v251, v251
	v_add_f32_e32 v228, 0, v116
	v_add_f32_e32 v229, 0, v100
	v_add_f32_e32 v228, v117, v228
	v_add_f32_e32 v229, v101, v229
	v_add_f32_e32 v228, v118, v228
	v_add_f32_e32 v229, v102, v229
	v_add_f32_e32 v228, v119, v228
	v_add_f32_e32 v229, v103, v229
	v_add_f32_e32 v228, v112, v228
	v_add_f32_e32 v229, v96, v229
	v_add_f32_e32 v228, v113, v228
	v_add_f32_e32 v229, v97, v229
	v_add_f32_e32 v228, v114, v228
	v_add_f32_e32 v229, v98, v229
	v_add_f32_e32 v228, v115, v228
	v_add_f32_e32 v229, v99, v229
	v_add_f32_e32 v228, v108, v228
	v_add_f32_e32 v229, v244, v229
	v_add_f32_e32 v228, v109, v228
	v_add_f32_e32 v229, v245, v229
	v_add_f32_e32 v228, v110, v228
	v_add_f32_e32 v229, v246, v229
	v_add_f32_e32 v228, v111, v228
	v_add_f32_e32 v229, v247, v229
	v_add_f32_e32 v228, v104, v228
	v_add_f32_e32 v229, v248, v229
	v_add_f32_e32 v228, v105, v228
	v_add_f32_e32 v229, v249, v229
	v_add_f32_e32 v228, v106, v228
	v_add_f32_e32 v229, v250, v229
	v_add_f32_e32 v228, v107, v228
	v_add_f32_e32 v229, v251, v229
	v_cvt_pk_bf16_f32 v76, v116, v117
	v_cvt_pk_bf16_f32 v77, v118, v119
	v_cvt_pk_bf16_f32 v78, v112, v113
	v_cvt_pk_bf16_f32 v79, v114, v115
	v_cvt_pk_bf16_f32 v84, v100, v101
	v_cvt_pk_bf16_f32 v85, v102, v103
	v_cvt_pk_bf16_f32 v86, v96, v97
	v_cvt_pk_bf16_f32 v87, v98, v99
	v_cvt_pk_bf16_f32 v72, v108, v109
	v_cvt_pk_bf16_f32 v73, v110, v111
	v_cvt_pk_bf16_f32 v74, v104, v105
	v_cvt_pk_bf16_f32 v75, v106, v107
	v_cvt_pk_bf16_f32 v80, v244, v245
	v_cvt_pk_bf16_f32 v81, v246, v247
	v_cvt_pk_bf16_f32 v82, v248, v249
	v_cvt_pk_bf16_f32 v83, v250, v251
	v_fma_f32 v225, v225, v232, v228
	v_fma_f32 v224, v224, v232, v229
	s_nop 1
	s_waitcnt lgkmcnt(7)
	v_mfma_f32_16x16x32_bf16 v[52:55], v[88:91], v[76:79], v[52:55]
	v_mfma_f32_16x16x32_bf16 v[36:39], v[88:91], v[84:87], v[36:39]
	s_waitcnt lgkmcnt(6)
	v_mfma_f32_16x16x32_bf16 v[52:55], v[92:95], v[72:75], v[52:55]
	v_mfma_f32_16x16x32_bf16 v[36:39], v[92:95], v[80:83], v[36:39]
	s_waitcnt lgkmcnt(5)
	v_mfma_f32_16x16x32_bf16 v[44:47], v[164:167], v[76:79], v[44:47]
	v_mfma_f32_16x16x32_bf16 v[28:31], v[164:167], v[84:87], v[28:31]
	s_waitcnt lgkmcnt(4)
	v_mfma_f32_16x16x32_bf16 v[44:47], v[168:171], v[72:75], v[44:47]
	v_mfma_f32_16x16x32_bf16 v[28:31], v[168:171], v[80:83], v[28:31]
	s_waitcnt lgkmcnt(3)
	v_mfma_f32_16x16x32_bf16 v[40:43], v[172:175], v[76:79], v[40:43]
	v_mfma_f32_16x16x32_bf16 v[16:19], v[172:175], v[84:87], v[16:19]
	s_waitcnt lgkmcnt(2)
	v_mfma_f32_16x16x32_bf16 v[40:43], v[236:239], v[72:75], v[40:43]
	v_mfma_f32_16x16x32_bf16 v[16:19], v[236:239], v[80:83], v[16:19]
	s_waitcnt lgkmcnt(1)
	v_mfma_f32_16x16x32_bf16 v[48:51], v[240:243], v[76:79], v[48:51]
	v_mfma_f32_16x16x32_bf16 v[32:35], v[240:243], v[84:87], v[32:35]
	s_waitcnt lgkmcnt(0)
	v_mfma_f32_16x16x32_bf16 v[48:51], v[160:163], v[72:75], v[48:51]
	v_mfma_f32_16x16x32_bf16 v[32:35], v[160:163], v[80:83], v[32:35]
	s_branch .LBB0_883
